# dilated block: silu(z) gate loads for the final merge issued at the run prologue (latency hidden behind the tile loop)
# speedup vs baseline: 1.1844x; 1.0029x over previous
.LBB0_271:
	s_cmp_gt_u32 s75, 1
	s_cselect_b64 s[26:27], -1, 0
	s_min_u32 s6, s75, 2
	s_lshl_b32 s76, s6, 1
	s_lshr_b32 s78, 0x2000, s76
	s_add_i32 s79, s78, -1
	s_cmp_lg_u32 s75, 0
	s_cselect_b64 s[24:25], -1, 0
	s_lshl_b32 s6, s75, 3
	s_add_i32 s6, s70, s6
	s_cmp_eq_u32 s75, 1
	s_cselect_b32 s6, s71, s6
	s_cselect_b32 s7, s73, s72
	s_cmp_eq_u32 s75, 0
	s_cselect_b32 s77, 0, s6
	s_cselect_b32 s80, s74, s7
	s_lshl_b32 s6, 1, s76
	s_cmp_lt_u32 s75, 2
	v_cvt_f32_ubyte0_e32 v6, s6
	v_or_b32_e32 v2, s80, v200
	v_add_u32_e32 v225, s80, v204
	s_cselect_b64 s[6:7], -1, 0
	v_lshlrev_b32_e32 v0, s76, v2
	v_cndmask_b32_e64 v2, v2, v225, s[6:7]
	v_add_u32_e32 v190, s77, v0
	v_lshlrev_b32_e32 v2, s76, v2
	v_ashrrev_i32_e32 v191, 31, v190
	v_add_u32_e32 v2, s77, v2
	v_lshlrev_b64 v[0:1], 7, v[190:191]
	v_ashrrev_i32_e32 v3, 31, v2
	v_lshl_add_u64 v[0:1], v[182:183], 0, v[0:1]
	v_lshlrev_b64 v[2:3], 7, v[2:3]
	v_add_u32_e32 v7, s80, v205
	v_lshl_add_u64 v[2:3], v[182:183], 0, v[2:3]
	s_cmp_lt_u32 s75, 2
	s_cbranch_scc1 .Lzs_skip
	v_lshl_add_u64 v[170:171], v[190:191], 0, s[20:21]
	v_lshlrev_b64 v[170:171], 10, v[170:171]
	v_lshl_add_u64 v[170:171], v[170:171], 0, s[22:23]
	v_lshlrev_b64 v[170:171], 1, v[170:171]
	v_lshl_add_u64 v[172:173], v[186:187], 0, v[170:171]
	global_load_dwordx2 v[238:239], v[172:173], off
	global_load_dwordx2 v[240:241], v[172:173], off offset:16
	global_load_dwordx2 v[242:243], v[172:173], off offset:32
	global_load_dwordx2 v[244:245], v[172:173], off offset:48
	global_load_dwordx2 v[246:247], v[172:173], off offset:64
	global_load_dwordx2 v[248:249], v[172:173], off offset:80
	global_load_dwordx2 v[250:251], v[172:173], off offset:96
	global_load_dwordx2 v[252:253], v[172:173], off offset:112
.Lzs_skip:
	global_load_dwordx4 v[80:83], v[0:1], off
	global_load_dwordx4 v[84:87], v[0:1], off offset:32
	global_load_dwordx4 v[88:91], v[2:3], off
	global_load_dwordx4 v[92:95], v[2:3], off offset:32
	global_load_dwordx4 v[96:99], v[0:1], off offset:64
	global_load_dwordx4 v[100:103], v[0:1], off offset:96
	v_min_i32_e32 v0, s79, v7
	v_cmp_gt_i32_e32 vcc, 0, v7
	s_and_b64 s[28:29], s[6:7], exec
	s_cselect_b32 s81, 6, 5
	v_cndmask_b32_e64 v0, v0, 0, vcc
	v_lshlrev_b32_e32 v0, s76, v0
	v_add_u32_e32 v0, s77, v0
	v_ashrrev_i32_e32 v1, 31, v0
	v_lshlrev_b64 v[0:1], 7, v[0:1]
	v_lshl_add_u64 v[4:5], v[128:129], 0, v[0:1]
	v_lshl_add_u64 v[0:1], v[184:185], 0, v[0:1]
	global_load_dwordx4 v[68:71], v[4:5], off
	global_load_dwordx4 v[64:67], v[0:1], off
	v_or_b32_e32 v0, 8, v7
	v_min_i32_e32 v0, s79, v0
	v_cndmask_b32_e64 v0, v0, 0, vcc
	v_lshlrev_b32_e32 v0, s76, v0
	v_add_u32_e32 v0, s77, v0
	v_ashrrev_i32_e32 v1, 31, v0
	v_lshlrev_b64 v[0:1], 7, v[0:1]
	v_lshl_add_u64 v[4:5], v[128:129], 0, v[0:1]
	v_lshl_add_u64 v[0:1], v[184:185], 0, v[0:1]
	global_load_dwordx4 v[76:79], v[4:5], off
	global_load_dwordx4 v[72:75], v[0:1], off
	v_or_b32_e32 v0, 16, v7
	v_min_i32_e32 v0, s79, v0
	v_cndmask_b32_e64 v0, v0, 0, vcc
	v_lshlrev_b32_e32 v0, s76, v0
	v_add_u32_e32 v0, s77, v0
	v_ashrrev_i32_e32 v1, 31, v0
	v_lshlrev_b64 v[0:1], 7, v[0:1]
	v_lshl_add_u64 v[4:5], v[128:129], 0, v[0:1]
	v_lshl_add_u64 v[0:1], v[184:185], 0, v[0:1]
	global_load_dwordx4 v[152:155], v[4:5], off
	global_load_dwordx4 v[148:151], v[0:1], off
	v_or_b32_e32 v0, 24, v7
	v_min_i32_e32 v0, s79, v0
	v_cndmask_b32_e64 v0, v0, 0, vcc
	v_lshlrev_b32_e32 v0, s76, v0
	v_add_u32_e32 v0, s77, v0
	v_ashrrev_i32_e32 v1, 31, v0
	v_lshlrev_b64 v[0:1], 7, v[0:1]
	v_lshl_add_u64 v[4:5], v[128:129], 0, v[0:1]
	v_lshl_add_u64 v[0:1], v[184:185], 0, v[0:1]
	global_load_dwordx4 v[160:163], v[4:5], off
	global_load_dwordx4 v[156:159], v[0:1], off
	global_load_dwordx4 v[104:107], v[2:3], off offset:64
	global_load_dwordx4 v[108:111], v[2:3], off offset:96
	v_mov_b32_e32 v227, 0
	v_mul_f32_e64 v228, v203, -v6
	s_lshl_b32 s82, s81, 5
	v_add_u32_e32 v229, s80, v202
	s_xor_b64 s[36:37], s[6:7], -1
	s_mov_b32 s83, 0
	v_mov_b32_e32 v226, 0
	s_mov_b32 s85, 0
	v_mov_b32_e32 v16, 0
	v_mov_b32_e32 v17, v227
	v_mov_b32_e32 v18, v227
	v_mov_b32_e32 v19, v227
	v_mov_b32_e32 v20, v227
	v_mov_b32_e32 v21, v227
	v_mov_b32_e32 v22, v227
	v_mov_b32_e32 v23, v227
	v_mov_b32_e32 v24, v227
	v_mov_b32_e32 v25, v227
	v_mov_b32_e32 v26, v227
	v_mov_b32_e32 v27, v227
	v_mov_b32_e32 v28, v227
	v_mov_b32_e32 v29, v227
	v_mov_b32_e32 v30, v227
	v_mov_b32_e32 v31, v227
	v_mov_b32_e32 v0, 0
	v_mov_b32_e32 v1, v227
	v_mov_b32_e32 v2, v227
	v_mov_b32_e32 v3, v227
	v_mov_b32_e32 v4, v227
	v_mov_b32_e32 v5, v227
	v_mov_b32_e32 v6, v227
	v_mov_b32_e32 v7, v227
	v_mov_b32_e32 v8, v227
	v_mov_b32_e32 v9, v227
	v_mov_b32_e32 v10, v227
	v_mov_b32_e32 v11, v227
	v_mov_b32_e32 v12, v227
	v_mov_b32_e32 v13, v227
	v_mov_b32_e32 v14, v227
	v_mov_b32_e32 v15, v227
	v_mov_b32_e32 v48, 0
	v_mov_b32_e32 v49, v227
	v_mov_b32_e32 v50, v227
	v_mov_b32_e32 v51, v227
	v_mov_b32_e32 v52, v227
	v_mov_b32_e32 v53, v227
	v_mov_b32_e32 v54, v227
	v_mov_b32_e32 v55, v227
	s_waitcnt vmcnt(9)
	v_mov_b64_e32 v[118:119], v[70:71]
	s_waitcnt vmcnt(8)
	v_mov_b64_e32 v[114:115], v[66:67]
	v_mov_b32_e32 v56, v227
	v_mov_b32_e32 v57, v227
	v_mov_b32_e32 v58, v227
	v_mov_b32_e32 v59, v227
	v_mov_b32_e32 v60, v227
	v_mov_b32_e32 v61, v227
	v_mov_b32_e32 v62, v227
	v_mov_b32_e32 v63, v227
	s_waitcnt vmcnt(7)
	v_mov_b64_e32 v[126:127], v[78:79]
	s_waitcnt vmcnt(6)
	v_mov_b64_e32 v[122:123], v[74:75]
	v_mov_b32_e32 v32, v227
	v_mov_b32_e32 v33, v227
	v_mov_b32_e32 v34, v227
	v_mov_b32_e32 v35, v227
	v_mov_b32_e32 v36, v227
	v_mov_b32_e32 v37, v227
	v_mov_b32_e32 v38, v227
	v_mov_b32_e32 v39, v227
	s_waitcnt vmcnt(5)
	v_mov_b64_e32 v[136:137], v[152:153]
	s_waitcnt vmcnt(4)
	v_mov_b64_e32 v[132:133], v[148:149]
	v_mov_b32_e32 v40, v227
	v_mov_b32_e32 v41, v227
	v_mov_b32_e32 v42, v227
	v_mov_b32_e32 v43, v227
	v_mov_b32_e32 v44, v227
	v_mov_b32_e32 v45, v227
	s_waitcnt vmcnt(3)
	v_mov_b64_e32 v[144:145], v[160:161]
	s_waitcnt vmcnt(2)
	v_mov_b64_e32 v[140:141], v[156:157]
	v_mov_b32_e32 v46, v227
	v_mov_b32_e32 v47, v227
	v_mov_b64_e32 v[112:113], v[64:65]
	v_mov_b64_e32 v[120:121], v[72:73]
	v_mov_b64_e32 v[134:135], v[150:151]
	v_mov_b64_e32 v[142:143], v[158:159]
	v_mov_b64_e32 v[116:117], v[68:69]
	v_mov_b64_e32 v[124:125], v[76:77]
	v_mov_b64_e32 v[138:139], v[154:155]
	v_mov_b64_e32 v[146:147], v[162:163]
	s_add_i32 s84, s85, 1
	s_cmp_ge_u32 s84, s81
	s_cbranch_scc1 .LBB0_273

.LBB0_285:
	s_waitcnt vmcnt(0)
	v_lshl_add_u64 v[74:75], v[190:191], 0, s[20:21]
	v_lshlrev_b64 v[74:75], 10, v[74:75]
	v_lshl_add_u64 v[74:75], v[74:75], 0, s[22:23]
	v_lshlrev_b64 v[74:75], 1, v[74:75]
	v_lshl_add_u64 v[76:77], v[186:187], 0, v[74:75]
	v_mov_b64_e32 v[78:79], v[238:239]
	v_mov_b64_e32 v[80:81], v[240:241]
	v_mov_b64_e32 v[82:83], v[242:243]
	v_mov_b64_e32 v[84:85], v[244:245]
	v_mov_b64_e32 v[86:87], v[246:247]
	v_mov_b64_e32 v[88:89], v[248:249]
	v_mov_b64_e32 v[90:91], v[250:251]
	v_div_scale_f32 v92, s[26:27], v70, v70, 1.0
	v_mov_b64_e32 v[76:77], v[252:253]
	v_rcp_f32_e32 v93, v92
	v_div_scale_f32 v94, vcc, 1.0, v70, 1.0
	v_lshl_add_u64 v[74:75], v[188:189], 0, v[74:75]
	v_fma_f32 v95, -v92, v93, 1.0
	v_fmac_f32_e32 v93, v95, v93
	v_mul_f32_e32 v95, v94, v93
	v_fma_f32 v96, -v92, v95, v94
	v_fmac_f32_e32 v95, v96, v93
	v_fma_f32 v92, -v92, v95, v94
	v_div_fmas_f32 v92, v92, v93, v95
	v_div_fixup_f32 v92, v92, v70, 1.0
	v_pk_mul_f32 v[94:95], v[48:49], v[92:93] op_sel_hi:[1,0]
	v_pk_mul_f32 v[96:97], v[50:51], v[92:93] op_sel_hi:[1,0]
	v_pk_mul_f32 v[98:99], v[52:53], v[92:93] op_sel_hi:[1,0]
	v_pk_mul_f32 v[100:101], v[54:55], v[92:93] op_sel_hi:[1,0]
	v_pk_mul_f32 v[102:103], v[56:57], v[92:93] op_sel_hi:[1,0]
	v_pk_mul_f32 v[104:105], v[58:59], v[92:93] op_sel_hi:[1,0]
	v_pk_mul_f32 v[106:107], v[60:61], v[92:93] op_sel_hi:[1,0]
	v_pk_mul_f32 v[108:109], v[62:63], v[92:93] op_sel_hi:[1,0]
	v_pk_mul_f32 v[110:111], v[32:33], v[92:93] op_sel_hi:[1,0]
	v_pk_mul_f32 v[112:113], v[34:35], v[92:93] op_sel_hi:[1,0]
	v_pk_mul_f32 v[116:117], v[38:39], v[92:93] op_sel_hi:[1,0]
	v_pk_mul_f32 v[114:115], v[36:37], v[92:93] op_sel_hi:[1,0]
	v_lshlrev_b32_e32 v118, 16, v78
	v_and_b32_e32 v119, 0xffff0000, v78
	v_lshlrev_b32_e32 v78, 16, v79
	v_and_b32_e32 v79, 0xffff0000, v79
	v_lshlrev_b32_e32 v120, 16, v80
	v_and_b32_e32 v121, 0xffff0000, v80
	v_lshlrev_b32_e32 v80, 16, v81
	v_and_b32_e32 v81, 0xffff0000, v81
	v_lshlrev_b32_e32 v122, 16, v82
	v_and_b32_e32 v123, 0xffff0000, v82
	v_lshlrev_b32_e32 v82, 16, v83
	v_and_b32_e32 v83, 0xffff0000, v83
	v_lshlrev_b32_e32 v124, 16, v84
	v_and_b32_e32 v125, 0xffff0000, v84
	v_lshlrev_b32_e32 v84, 16, v85
	v_and_b32_e32 v85, 0xffff0000, v85
	v_lshlrev_b32_e32 v126, 16, v86
	v_and_b32_e32 v127, 0xffff0000, v86
	v_lshlrev_b32_e32 v86, 16, v87
	v_and_b32_e32 v87, 0xffff0000, v87
	v_pk_mul_f32 v[94:95], v[94:95], v[118:119]
	v_pk_mul_f32 v[78:79], v[96:97], v[78:79]
	v_pk_mul_f32 v[96:97], v[98:99], v[120:121]
	v_pk_mul_f32 v[80:81], v[100:101], v[80:81]
	v_pk_mul_f32 v[98:99], v[102:103], v[122:123]
	v_pk_mul_f32 v[82:83], v[104:105], v[82:83]
	v_pk_mul_f32 v[100:101], v[106:107], v[124:125]
	v_pk_mul_f32 v[84:85], v[108:109], v[84:85]
	v_pk_mul_f32 v[102:103], v[110:111], v[126:127]
	v_pk_mul_f32 v[86:87], v[112:113], v[86:87]
	v_cvt_pk_bf16_f32 v94, v94, v95
	v_cvt_pk_bf16_f32 v95, v78, v79
	v_cvt_pk_bf16_f32 v78, v96, v97
	v_cvt_pk_bf16_f32 v79, v80, v81
	v_cvt_pk_bf16_f32 v80, v98, v99
	v_cvt_pk_bf16_f32 v81, v82, v83
	v_cvt_pk_bf16_f32 v82, v100, v101
	v_cvt_pk_bf16_f32 v83, v84, v85
	v_cvt_pk_bf16_f32 v84, v102, v103
	v_cvt_pk_bf16_f32 v85, v86, v87
	global_store_dwordx2 v[74:75], v[94:95], off
	global_store_dwordx2 v[74:75], v[78:79], off offset:16
	global_store_dwordx2 v[74:75], v[80:81], off offset:32
	global_store_dwordx2 v[74:75], v[82:83], off offset:48
	global_store_dwordx2 v[74:75], v[84:85], off offset:64
	v_lshlrev_b32_e32 v78, 16, v89
	v_and_b32_e32 v79, 0xffff0000, v89
	v_pk_mul_f32 v[78:79], v[116:117], v[78:79]
	v_lshlrev_b32_e32 v80, 16, v90
	v_cvt_pk_bf16_f32 v87, v78, v79
	v_pk_mul_f32 v[78:79], v[40:41], v[92:93] op_sel_hi:[1,0]
	v_and_b32_e32 v81, 0xffff0000, v90
	v_pk_mul_f32 v[78:79], v[78:79], v[80:81]
	v_pk_mul_f32 v[80:81], v[42:43], v[92:93] op_sel_hi:[1,0]
	v_lshlrev_b32_e32 v82, 16, v91
	v_and_b32_e32 v83, 0xffff0000, v91
	v_pk_mul_f32 v[80:81], v[80:81], v[82:83]
	v_cvt_pk_bf16_f32 v78, v78, v79
	v_cvt_pk_bf16_f32 v79, v80, v81
	global_store_dwordx2 v[74:75], v[78:79], off offset:96
	v_pk_mul_f32 v[78:79], v[44:45], v[92:93] op_sel_hi:[1,0]
	v_lshlrev_b32_e32 v80, 16, v76
	v_and_b32_e32 v81, 0xffff0000, v76
	v_pk_mul_f32 v[78:79], v[78:79], v[80:81]
	v_lshlrev_b32_e32 v132, 16, v88
	v_and_b32_e32 v133, 0xffff0000, v88
	v_cvt_pk_bf16_f32 v76, v78, v79
	v_pk_mul_f32 v[78:79], v[46:47], v[92:93] op_sel_hi:[1,0]
	v_lshlrev_b32_e32 v80, 16, v77
	v_and_b32_e32 v81, 0xffff0000, v77
	v_pk_mul_f32 v[104:105], v[114:115], v[132:133]
	v_pk_mul_f32 v[78:79], v[78:79], v[80:81]
	v_cvt_pk_bf16_f32 v86, v104, v105
	v_cvt_pk_bf16_f32 v77, v78, v79
	global_store_dwordx2 v[74:75], v[86:87], off offset:80
	global_store_dwordx2 v[74:75], v[76:77], off offset:112
	s_cbranch_execnz .LBB0_282
